# comb1 + conv row-load fast path + gMLP LN/out-norm tables in LDS (v2 register plan)
# speedup vs baseline: 1.0036x; 1.0024x over previous
; #define LAS __attribute__((address_space(3)))
; __global__ void __launch_bounds__(NTHR, 2) fwd_megakernel(Args args) {
;     ...
;             const int tc0 = (su >> 2) * 128, qi = su & 3, i0 = 32 * qi, J = qi < 2 ? 64 : 128;
;             constexpr int LDB = 136;
;             LAS bf16_t* Bt = (LAS bf16_t*)lds;
;             LAS f32x2* st = (LAS f32x2*)(lds + 2 * 128 * LDB * 2);
;             LAS float* red = (LAS float*)(lds + 2 * 128 * LDB * 2 + 1024);
;             if (tid < J) { const f32x4* p = (const f32x4*)(VSTAT + (size_t)(tc0 + tid) * 32); float s1 = 0.f, s2 = 0.f;
; #pragma unroll
;                 for (int j = 0; j < 8; ++j) { const f32x4 v = p[j]; s1 += v[0] + v[2]; s2 += v[1] + v[3]; }
;                 const float mean = s1 * (1.0f / CCH), var = fmaxf(s2 * (1.0f / CCH) - mean * mean, 0.f); st[tid] = (f32x2){mean, rsqrtf(var + LN_EPS)}; }
;             const int mb = wave & 1, nq = wave >> 1, fr = lane & 15, fq = lane >> 4;
;             const int trow = tc0 + i0 + 16 * mb + fr;
;             const float* lng = KIN(I_SGU_LN_G); const float* lnb = KIN(I_SGU_LN_B); const float* sgb = KIN(I_SGU_B);
;             const int c8 = tid & 15, jb = tid >> 4, nk = J / 32;
;             u32x4 pv[4]; f32x4 pg0, pg1, pb0, pb1; bf16x8 pw[4]; u32x2 pu0, pu1; float pbs;
;     ...
;             f32x4 yv[8][2]; float ss = 0.f;
;             SGU_PREFETCH(0);
;             __syncthreads();
; #pragma unroll
;             for (int h = 0; h < 8; ++h) {
;                 LAS bf16_t* Bc = Bt + (h & 1) * (128 * LDB);
; #pragma unroll
;                 for (int k = 0; k < 4; ++k) if (k < nk) { const int j = jb + 32 * k; const u32x4 v = pv[k]; const f32x2 ms = st[j];
;                     const f32x4 x0 = (f32x4){bf_lo(v.x), bf_hi(v.x), bf_lo(v.y), bf_hi(v.y)}, x1 = (f32x4){bf_lo(v.z), bf_hi(v.z), bf_lo(v.w), bf_hi(v.w)};
;                     const f32x4 y0 = (x0 - ms.x) * ms.y * pg0 + pb0, y1 = (x1 - ms.x) * ms.y * pg1 + pb1;
;                     LAS bf16_t* d = Bc + (c8 * 8) * LDB + (j ^ (8 * c8));
;                     const unsigned p0 = cvt_pk_bf16(y0[0], y0[1]), p1 = cvt_pk_bf16(y0[2], y0[3]), p2 = cvt_pk_bf16(y1[0], y1[1]), p3 = cvt_pk_bf16(y1[2], y1[3]);
;                     d[0 * LDB] = (bf16_t)(p0 & 0xffffu); d[1 * LDB] = (bf16_t)(p0 >> 16); d[2 * LDB] = (bf16_t)(p1 & 0xffffu); d[3 * LDB] = (bf16_t)(p1 >> 16);
.LBB0_657:
	v_readlane_b32 s2, v254, 3
	s_add_i32 s11, 0, 0x11000
	s_bfe_u32 s4, s2, 0x10006
	s_lshr_b32 s5, s2, 7
	v_and_b32_e32 v2, 15, v221
	s_add_u32 s2, s0, s42
	v_mov_b32_e32 v121, 0
	v_lshl_or_b32 v155, s4, 4, v2
	s_addc_u32 s3, s1, s43
	v_and_b32_e32 v0, 48, v220
	v_mov_b32_e32 v1, v121
	s_lshl_b32 s4, s4, 8
	s_load_dwordx4 s[24:27], s[2:3], 0x58
	s_load_dwordx2 s[20:21], s[2:3], 0x70
	s_load_dwordx2 s[100:101], s[2:3], 0x80
	v_lshl_add_u64 v[0:1], s[14:15], 0, v[0:1]
	s_mov_b64 s[2:3], 0xbc00000
	s_add_i32 s4, s4, 0
	v_lshl_add_u64 v[128:129], v[0:1], 0, s[2:3]
	s_lshl_b32 s18, s5, 5
	v_mov_b32_e32 v0, 0x68
	s_add_i32 s4, s4, 0x11400
	s_lshl_b32 s5, s5, 6
	v_lshlrev_b32_e32 v120, 4, v2
	v_bitop3_b32 v7, s18, v0, v2 bitop3:0xc8
	s_add_i32 s23, s4, s5
	v_lshlrev_b32_e32 v0, 2, v2
	v_lshrrev_b32_e32 v3, 4, v220
	v_lshl_add_u64 v[122:123], s[36:37], 0, v[120:121]
	v_lshlrev_b32_e32 v120, 5, v2
	v_add_u32_e32 v175, s4, v0
	s_add_u32 s4, s88, s5
	s_waitcnt lgkmcnt(0)
	v_lshl_add_u64 v[124:125], s[24:25], 0, v[120:121]
	v_lshl_add_u64 v[126:127], s[26:27], 0, v[120:121]
	v_lshlrev_b32_e32 v120, 3, v3
	s_addc_u32 s5, s89, 0
	v_lshrrev_b32_e32 v163, 4, v221
	v_lshlrev_b32_e32 v4, 3, v2
	v_lshl_add_u64 v[130:131], s[4:5], 0, v[120:121]
	s_movk_i32 s4, 0x880
	v_or_b32_e32 v1, s18, v2
	v_add_u32_e32 v169, s23, v0
	v_lshl_or_b32 v0, v3, 2, s18
	v_mad_u32_u24 v2, v2, s4, 0
	v_xor_b32_e32 v3, v163, v4
	v_lshl_add_u32 v186, v3, 1, v2
	v_add_u32_e32 v3, 32, v163
	v_lshl_add_u32 v187, v3, 3, s11
	v_xor_b32_e32 v3, v3, v4
	v_lshl_add_u32 v188, v3, 1, v2
	v_or_b32_e32 v3, 64, v163
	v_lshl_add_u32 v189, v3, 3, s11
	v_bitop3_b32 v3, v163, v4, 64 bitop3:0x36
	s_movk_i32 s2, 0x110
	v_lshl_add_u32 v190, v3, 1, v2
	v_add_u32_e32 v3, 0x60, v163
	v_mul_lo_u32 v6, v1, s2
	s_movk_i32 s19, 0x68
	s_movk_i32 s22, 0x78
	v_lshl_add_u32 v191, v3, 3, s11
	v_xor_b32_e32 v3, v3, v4
	v_or_b32_e32 v5, 16, v1
	v_bitop3_b32 v8, v1, s22, 16 bitop3:0xc8
	v_lshl_add_u32 v192, v3, 1, v2
	v_add_u32_e32 v2, 0, v6
	v_bitop3_b32 v1, v120, v1, s19 bitop3:0x78
	v_add_u32_e32 v3, 0x1100, v2
	v_lshl_add_u32 v193, v1, 1, v2
	v_bitop3_b32 v1, v120, v5, s22 bitop3:0x78
	v_lshl_add_u32 v194, v1, 1, v3
	v_bitop3_b32 v1, v120, v7, 32 bitop3:0x36
	v_lshl_add_u32 v195, v1, 1, v2
	v_bitop3_b32 v1, v120, v8, 32 bitop3:0x36
	v_lshl_add_u32 v196, v1, 1, v3
	v_bitop3_b32 v1, v120, v7, 64 bitop3:0x36
	s_movk_i32 s4, 0x60
	v_lshl_add_u32 v197, v1, 1, v2
	v_bitop3_b32 v1, v120, v8, 64 bitop3:0x36
	v_lshl_add_u32 v198, v1, 1, v3
	v_bitop3_b32 v1, v120, v7, s4 bitop3:0x36
	v_lshl_add_u32 v199, v1, 1, v2
	v_bitop3_b32 v1, v120, v8, s4 bitop3:0x36
	v_lshlrev_b32_e32 v120, 1, v0
	v_lshl_add_u32 v137, v221, 3, s11
	v_cmp_gt_u32_e64 s[2:3], 16, v220
	v_lshl_add_u32 v181, v163, 3, s11
	v_lshl_add_u32 v200, v1, 1, v3
	v_lshl_add_u64 v[132:133], s[6:7], 0, v[120:121]
	s_lshl_b32 s23, s10, 5
	s_lshl_b32 s56, s34, 5
	s_mov_b32 s22, 0x3a800000
	s_mov_b32 s57, 0x800000
	v_and_b32_e32 v238, 0xff, v221
	v_lshlrev_b32_e32 v238, 4, v238
	v_mov_b32_e32 v239, 0
	v_lshl_add_u64 v[214:215], s[100:101], 0, v[238:239]
	v_cmp_gt_u32_e32 vcc, 0x100, v221
	v_mov_b32_e32 v240, s26
	v_mov_b32_e32 v241, s27
	v_mov_b32_e32 v242, s24
	v_mov_b32_e32 v243, s25
	s_nop 1
	v_cndmask_b32_e32 v240, v240, v242, vcc
	v_cndmask_b32_e32 v241, v241, v243, vcc
	v_lshl_add_u64 v[212:213], v[240:241], 0, v[238:239]
	v_and_b32_e32 v203, 15, v221
	v_lshlrev_b32_e32 v203, 5, v203
	v_add_u32_e32 v203, 0x11600, v203
	s_mov_b64 s[24:25], 0x10000
	v_mov_b32_e32 v201, 0x358637bd
	v_lshlrev_b32_e32 v202, 2, v0
	s_nop 0
	s_mov_b32 s58, s10
	s_branch .LBB0_659
.LBB0_658:
	s_or_b64 exec, exec, s[4:5]
	s_waitcnt lgkmcnt(0)
	v_add_u32_e32 v242, 0x13600, v202
	ds_read_b128 v[90:93], v242
	ds_read_b128 v[94:97], v242 offset:64
	ds_read_b128 v[98:101], v242 offset:512
	ds_read_b128 v[102:105], v242 offset:576
	ds_read_b128 v[106:109], v242 offset:1024
	ds_read_b128 v[110:113], v242 offset:1088
	ds_read_b128 v[114:117], v242 offset:1536
	ds_read_b128 v[138:141], v242 offset:1600
	ds_read_b128 v[142:145], v242 offset:2048
	ds_read_b128 v[146:149], v242 offset:2112
	ds_read_b128 v[150:153], v242 offset:2560
	ds_read_b128 v[222:225], v242 offset:2624
	ds_read_b128 v[226:229], v242 offset:3072
	ds_read_b128 v[230:233], v242 offset:3136
	ds_read_b128 v[234:237], v242 offset:3584
	ds_read_b128 v[238:241], v242 offset:3648
	s_barrier
; __device__ __forceinline__ unsigned cvt_pk_bf16(float lo, float hi) { unsigned r; asm volatile("v_cvt_pk_bf16_f32 %0, %1, %2" : "=v"(r) : "v"(lo), "v"(hi)); return r; }
; #define KIN(i) (*(const float* const __attribute__((address_space(4)))*)(kp + kz + 8 * (i)))
; __global__ void __launch_bounds__(NTHR, 2) fwd_megakernel(Args args) {
;     ...
;             ss += __shfl_xor(ss, 16); ss += __shfl_xor(ss, 32);
;             if (fq == 0) red[(mb * 4 + nq) * 16 + fr] = ss;
;             __syncthreads();
;             const float tot = (red[(mb * 4 + 0) * 16 + fr] + red[(mb * 4 + 1) * 16 + fr]) + (red[(mb * 4 + 2) * 16 + fr] + red[(mb * 4 + 3) * 16 + fr]);
;             const float r2 = rsqrtf(tot * (1.0f / CCH) + RMS_EPS);
; #pragma unroll
;             for (int h = 0; h < 8; ++h)
; #pragma unroll
;                 for (int nb = 0; nb < 2; ++nb) { const int ch = h * 128 + 32 * nq + 16 * nb + 4 * fq; const f32x4 gg = *(const f32x4*)(KIN(I_OUT_NORM_SGU) + ch); const f32x4 y = yv[h][nb] * r2 * gg;
;                     u32x2 w; w.x = cvt_pk_bf16(y[0], y[1]); w.y = cvt_pk_bf16(y[2], y[3]); *(u32x2*)(Y + (size_t)trow * D + CCH + ch) = w; }
	s_add_i32 s58, s58, s34
	s_add_i32 s23, s23, s56
	s_cmpk_lt_i32 s58, 0x100
	ds_read2_b32 v[72:73], v175 offset1:16
	ds_read2_b32 v[74:75], v175 offset0:32 offset1:48
	s_waitcnt lgkmcnt(1)
	v_mov_b32_e32 v78, v72
	s_waitcnt lgkmcnt(0)
	v_mov_b32_e32 v79, v74
	v_mov_b32_e32 v74, v73
	v_pk_add_f32 v[72:73], v[78:79], v[74:75]
	s_nop 0
	v_add_f32_e32 v72, v72, v73
	v_fmamk_f32 v72, v72, 0x3a800000, v201
	v_mul_f32_e32 v73, 0x4b800000, v72
	v_cmp_gt_f32_e32 vcc, s57, v72
	s_nop 1
	v_cndmask_b32_e32 v72, v72, v73, vcc
	v_rsq_f32_e32 v74, v72
	v_lshlrev_b64 v[72:73], 12, v[134:135]
	v_lshl_add_u64 v[72:73], v[132:133], 0, v[72:73]
	v_mul_f32_e32 v75, 0x45800000, v74
	v_cndmask_b32_e32 v74, v74, v75, vcc
	v_pk_mul_f32 v[0:1], v[74:75], v[14:15] op_sel_hi:[0,1]
	v_pk_mul_f32 v[2:3], v[74:75], v[12:13] op_sel_hi:[0,1]
	v_pk_mul_f32 v[0:1], v[90:91], v[0:1]
	v_pk_mul_f32 v[2:3], v[92:93], v[2:3]
	v_cvt_pk_bf16_f32 v0, v0, v1
	v_cvt_pk_bf16_f32 v1, v2, v3
	global_store_dwordx2 v[72:73], v[0:1], off offset:2048
	v_pk_mul_f32 v[4:5], v[74:75], v[10:11] op_sel_hi:[0,1]
	v_pk_mul_f32 v[6:7], v[74:75], v[8:9] op_sel_hi:[0,1]
	v_pk_mul_f32 v[4:5], v[94:95], v[4:5]
	v_pk_mul_f32 v[6:7], v[96:97], v[6:7]
	v_cvt_pk_bf16_f32 v4, v4, v5
	v_cvt_pk_bf16_f32 v5, v6, v7
	global_store_dwordx2 v[72:73], v[4:5], off offset:2080
	v_pk_mul_f32 v[0:1], v[74:75], v[80:81] op_sel_hi:[0,1]
	v_pk_mul_f32 v[2:3], v[74:75], v[20:21] op_sel_hi:[0,1]
	v_pk_mul_f32 v[0:1], v[98:99], v[0:1]
	v_pk_mul_f32 v[2:3], v[100:101], v[2:3]
	v_cvt_pk_bf16_f32 v0, v0, v1
	v_cvt_pk_bf16_f32 v1, v2, v3
	global_store_dwordx2 v[72:73], v[0:1], off offset:2304
	v_pk_mul_f32 v[4:5], v[74:75], v[18:19] op_sel_hi:[0,1]
	v_pk_mul_f32 v[6:7], v[74:75], v[16:17] op_sel_hi:[0,1]
	v_pk_mul_f32 v[4:5], v[102:103], v[4:5]
	v_pk_mul_f32 v[6:7], v[104:105], v[6:7]
	v_cvt_pk_bf16_f32 v4, v4, v5
	v_cvt_pk_bf16_f32 v5, v6, v7
	global_store_dwordx2 v[72:73], v[4:5], off offset:2336
	v_pk_mul_f32 v[0:1], v[74:75], v[30:31] op_sel_hi:[0,1]
	v_pk_mul_f32 v[2:3], v[74:75], v[28:29] op_sel_hi:[0,1]
	v_pk_mul_f32 v[0:1], v[106:107], v[0:1]
	v_pk_mul_f32 v[2:3], v[108:109], v[2:3]
	v_cvt_pk_bf16_f32 v0, v0, v1
	v_cvt_pk_bf16_f32 v1, v2, v3
	global_store_dwordx2 v[72:73], v[0:1], off offset:2560
	v_pk_mul_f32 v[4:5], v[74:75], v[24:25] op_sel_hi:[0,1]
	v_pk_mul_f32 v[6:7], v[74:75], v[22:23] op_sel_hi:[0,1]
	v_pk_mul_f32 v[4:5], v[110:111], v[4:5]
	v_pk_mul_f32 v[6:7], v[112:113], v[6:7]
	v_cvt_pk_bf16_f32 v4, v4, v5
	v_cvt_pk_bf16_f32 v5, v6, v7
	global_store_dwordx2 v[72:73], v[4:5], off offset:2592
	v_pk_mul_f32 v[0:1], v[74:75], v[46:47] op_sel_hi:[0,1]
	v_pk_mul_f32 v[2:3], v[74:75], v[44:45] op_sel_hi:[0,1]
	v_pk_mul_f32 v[0:1], v[114:115], v[0:1]
	v_pk_mul_f32 v[2:3], v[116:117], v[2:3]
	v_cvt_pk_bf16_f32 v0, v0, v1
	v_cvt_pk_bf16_f32 v1, v2, v3
	global_store_dwordx2 v[72:73], v[0:1], off offset:2816
	v_pk_mul_f32 v[4:5], v[74:75], v[40:41] op_sel_hi:[0,1]
	v_pk_mul_f32 v[6:7], v[74:75], v[26:27] op_sel_hi:[0,1]
	v_pk_mul_f32 v[4:5], v[138:139], v[4:5]
	v_pk_mul_f32 v[6:7], v[140:141], v[6:7]
	v_cvt_pk_bf16_f32 v4, v4, v5
	v_cvt_pk_bf16_f32 v5, v6, v7
	global_store_dwordx2 v[72:73], v[4:5], off offset:2848
	v_pk_mul_f32 v[0:1], v[74:75], v[82:83] op_sel_hi:[0,1]
	v_pk_mul_f32 v[2:3], v[74:75], v[52:53] op_sel_hi:[0,1]
	v_pk_mul_f32 v[0:1], v[142:143], v[0:1]
	v_pk_mul_f32 v[2:3], v[144:145], v[2:3]
	v_cvt_pk_bf16_f32 v0, v0, v1
	v_cvt_pk_bf16_f32 v1, v2, v3
	global_store_dwordx2 v[72:73], v[0:1], off offset:3072
	v_pk_mul_f32 v[4:5], v[74:75], v[48:49] op_sel_hi:[0,1]
	v_pk_mul_f32 v[6:7], v[74:75], v[42:43] op_sel_hi:[0,1]
	v_pk_mul_f32 v[4:5], v[146:147], v[4:5]
	v_pk_mul_f32 v[6:7], v[148:149], v[6:7]
	v_cvt_pk_bf16_f32 v4, v4, v5
	v_cvt_pk_bf16_f32 v5, v6, v7
	global_store_dwordx2 v[72:73], v[4:5], off offset:3104
	v_pk_mul_f32 v[0:1], v[74:75], v[84:85] op_sel_hi:[0,1]
	v_pk_mul_f32 v[2:3], v[74:75], v[60:61] op_sel_hi:[0,1]
	v_pk_mul_f32 v[0:1], v[150:151], v[0:1]
	v_pk_mul_f32 v[2:3], v[152:153], v[2:3]
	v_cvt_pk_bf16_f32 v0, v0, v1
	v_cvt_pk_bf16_f32 v1, v2, v3
	global_store_dwordx2 v[72:73], v[0:1], off offset:3328
	v_pk_mul_f32 v[4:5], v[74:75], v[58:59] op_sel_hi:[0,1]
	v_pk_mul_f32 v[6:7], v[74:75], v[54:55] op_sel_hi:[0,1]
	v_pk_mul_f32 v[4:5], v[222:223], v[4:5]
	v_pk_mul_f32 v[6:7], v[224:225], v[6:7]
	v_cvt_pk_bf16_f32 v4, v4, v5
	v_cvt_pk_bf16_f32 v5, v6, v7
	global_store_dwordx2 v[72:73], v[4:5], off offset:3360
	v_pk_mul_f32 v[0:1], v[74:75], v[70:71] op_sel_hi:[0,1]
	v_pk_mul_f32 v[2:3], v[74:75], v[68:69] op_sel_hi:[0,1]
	v_pk_mul_f32 v[0:1], v[226:227], v[0:1]
	v_pk_mul_f32 v[2:3], v[228:229], v[2:3]
	v_cvt_pk_bf16_f32 v0, v0, v1
	v_cvt_pk_bf16_f32 v1, v2, v3
	global_store_dwordx2 v[72:73], v[0:1], off offset:3584
	v_pk_mul_f32 v[4:5], v[74:75], v[64:65] op_sel_hi:[0,1]
	v_pk_mul_f32 v[6:7], v[74:75], v[62:63] op_sel_hi:[0,1]
	v_pk_mul_f32 v[4:5], v[230:231], v[4:5]
	v_pk_mul_f32 v[6:7], v[232:233], v[6:7]
	v_cvt_pk_bf16_f32 v4, v4, v5
	v_cvt_pk_bf16_f32 v5, v6, v7
	global_store_dwordx2 v[72:73], v[4:5], off offset:3616
	v_pk_mul_f32 v[0:1], v[74:75], v[76:77] op_sel_hi:[0,1]
	v_pk_mul_f32 v[2:3], v[74:75], v[66:67] op_sel_hi:[0,1]
	v_pk_mul_f32 v[0:1], v[234:235], v[0:1]
	v_pk_mul_f32 v[2:3], v[236:237], v[2:3]
	v_cvt_pk_bf16_f32 v0, v0, v1
	v_cvt_pk_bf16_f32 v1, v2, v3
	global_store_dwordx2 v[72:73], v[0:1], off offset:3840
	v_pk_mul_f32 v[4:5], v[74:75], v[56:57] op_sel_hi:[0,1]
	v_pk_mul_f32 v[6:7], v[74:75], v[50:51] op_sel_hi:[0,1]
	v_pk_mul_f32 v[4:5], v[238:239], v[4:5]
	v_pk_mul_f32 v[6:7], v[240:241], v[6:7]
	v_cvt_pk_bf16_f32 v4, v4, v5
	v_cvt_pk_bf16_f32 v5, v6, v7
	global_store_dwordx2 v[72:73], v[4:5], off offset:3872
	s_barrier
	s_cbranch_scc0 .LBB0_775
; #define LAS __attribute__((address_space(3)))
; __global__ void __launch_bounds__(NTHR, 2) fwd_megakernel(Args args) {
;     ...
;         for (int su = bid; su < T / 32; su += G) {
;             const int tc0 = (su >> 2) * 128, qi = su & 3, i0 = 32 * qi, J = qi < 2 ? 64 : 128;
;             constexpr int LDB = 136;
;             LAS bf16_t* Bt = (LAS bf16_t*)lds;
;             LAS f32x2* st = (LAS f32x2*)(lds + 2 * 128 * LDB * 2);
;             LAS float* red = (LAS float*)(lds + 2 * 128 * LDB * 2 + 1024);
;             if (tid < J) { const f32x4* p = (const f32x4*)(VSTAT + (size_t)(tc0 + tid) * 32); float s1 = 0.f, s2 = 0.f;
; #pragma unroll
;                 for (int j = 0; j < 8; ++j) { const f32x4 v = p[j]; s1 += v[0] + v[2]; s2 += v[1] + v[3]; }
;                 const float mean = s1 * (1.0f / CCH), var = fmaxf(s2 * (1.0f / CCH) - mean * mean, 0.f); st[tid] = (f32x2){mean, rsqrtf(var + LN_EPS)}; }
.LBB0_659:
	global_load_dwordx4 v[240:243], v[212:213], off
	global_load_dwordx4 v[244:247], v[214:215], off
	s_and_b32 s11, s23, 0xffffff80
	s_and_b32 s44, s58, 3
	s_cmp_gt_u32 s44, 1
	s_cselect_b64 s[26:27], -1, 0
	s_and_b64 s[4:5], s[26:27], exec
	s_cselect_b32 s4, 0x80, 64
	v_cmp_gt_u32_e32 vcc, s4, v221
	s_and_saveexec_b64 s[4:5], vcc
	s_cbranch_execz .LBB0_661
	v_add_u32_e32 v8, s11, v221
	v_ashrrev_i32_e32 v9, 31, v8
	v_lshlrev_b64 v[8:9], 7, v[8:9]
	v_lshl_add_u64 v[44:45], s[38:39], 0, v[8:9]
	global_load_dwordx4 v[8:11], v[44:45], off
	global_load_dwordx4 v[12:15], v[44:45], off offset:16
	global_load_dwordx4 v[16:19], v[44:45], off offset:32
	global_load_dwordx4 v[20:23], v[44:45], off offset:48
	global_load_dwordx4 v[24:27], v[44:45], off offset:64
	global_load_dwordx4 v[28:31], v[44:45], off offset:80
	global_load_dwordx4 v[40:43], v[44:45], off offset:96
	s_nop 0
	global_load_dwordx4 v[44:47], v[44:45], off offset:112
	s_waitcnt vmcnt(7)
	v_pk_add_f32 v[8:9], v[8:9], v[10:11]
	s_waitcnt vmcnt(6)
	v_pk_add_f32 v[10:11], v[12:13], v[14:15]
	v_pk_add_f32 v[8:9], v[8:9], 0 op_sel_hi:[1,0]
	s_waitcnt vmcnt(5)
	v_pk_add_f32 v[12:13], v[16:17], v[18:19]
	v_pk_add_f32 v[8:9], v[8:9], v[10:11]
	s_waitcnt vmcnt(4)
	v_pk_add_f32 v[14:15], v[20:21], v[22:23]
	v_pk_add_f32 v[8:9], v[8:9], v[12:13]
	s_waitcnt vmcnt(3)
	v_pk_add_f32 v[16:17], v[24:25], v[26:27]
	v_pk_add_f32 v[8:9], v[8:9], v[14:15]
	s_waitcnt vmcnt(2)
	v_pk_add_f32 v[18:19], v[28:29], v[30:31]
	v_pk_add_f32 v[8:9], v[8:9], v[16:17]
	s_waitcnt vmcnt(1)
	v_pk_add_f32 v[20:21], v[40:41], v[42:43]
	v_pk_add_f32 v[8:9], v[8:9], v[18:19]
	s_waitcnt vmcnt(0)
	v_pk_add_f32 v[22:23], v[44:45], v[46:47]
	v_pk_add_f32 v[8:9], v[8:9], v[20:21]
	s_nop 0
	v_pk_add_f32 v[8:9], v[8:9], v[22:23]
	s_nop 0
	v_pk_mul_f32 v[8:9], v[8:9], s[22:23] op_sel_hi:[1,0]
	s_nop 0
	v_fma_f32 v9, -v8, v8, v9
	v_max_f32_e32 v9, 0, v9
	v_add_f32_e32 v9, 0x3727c5ac, v9
	v_mul_f32_e32 v10, 0x4b800000, v9
	v_cmp_gt_f32_e32 vcc, s57, v9
	s_nop 1
	v_cndmask_b32_e32 v9, v9, v10, vcc
	v_rsq_f32_e32 v9, v9
	s_nop 0
	v_mul_f32_e32 v10, 0x45800000, v9
	v_cndmask_b32_e32 v9, v9, v10, vcc
	ds_write_b64 v137, v[8:9]

; #define LAS __attribute__((address_space(3)))
; __device__ __forceinline__ unsigned cvt_pk_bf16(float lo, float hi) { unsigned r; asm volatile("v_cvt_pk_bf16_f32 %0, %1, %2" : "=v"(r) : "v"(lo), "v"(hi)); return r; }
; __device__ __forceinline__ float bf_lo(unsigned u) { return __uint_as_float(u << 16); }
; __device__ __forceinline__ float bf_hi(unsigned u) { return __uint_as_float(u & 0xffff0000u); }
; #define KIN(i) (*(const float* const __attribute__((address_space(4)))*)(kp + kz + 8 * (i)))
; __global__ void __launch_bounds__(NTHR, 2) fwd_megakernel(Args args) {
;     ...
;             const int trow = tc0 + i0 + 16 * mb + fr;
;             const float* lng = KIN(I_SGU_LN_G); const float* lnb = KIN(I_SGU_LN_B); const float* sgb = KIN(I_SGU_B);
;             const int c8 = tid & 15, jb = tid >> 4, nk = J / 32;
;             u32x4 pv[4]; f32x4 pg0, pg1, pb0, pb1; bf16x8 pw[4]; u32x2 pu0, pu1; float pbs;
;     ...
;             f32x4 yv[8][2]; float ss = 0.f;
;             SGU_PREFETCH(0);
;             __syncthreads();
; #pragma unroll
;             for (int h = 0; h < 8; ++h) {
;                 LAS bf16_t* Bc = Bt + (h & 1) * (128 * LDB);
; #pragma unroll
;                 for (int k = 0; k < 4; ++k) if (k < nk) { const int j = jb + 32 * k; const u32x4 v = pv[k]; const f32x2 ms = st[j];
;                     const f32x4 x0 = (f32x4){bf_lo(v.x), bf_hi(v.x), bf_lo(v.y), bf_hi(v.y)}, x1 = (f32x4){bf_lo(v.z), bf_hi(v.z), bf_lo(v.w), bf_hi(v.w)};
;                     const f32x4 y0 = (x0 - ms.x) * ms.y * pg0 + pb0, y1 = (x1 - ms.x) * ms.y * pg1 + pb1;
;                     LAS bf16_t* d = Bc + (c8 * 8) * LDB + (j ^ (8 * c8));
;                     const unsigned p0 = cvt_pk_bf16(y0[0], y0[1]), p1 = cvt_pk_bf16(y0[2], y0[3]), p2 = cvt_pk_bf16(y1[0], y1[1]), p3 = cvt_pk_bf16(y1[2], y1[3]);
;                     d[0 * LDB] = (bf16_t)(p0 & 0xffffu); d[1 * LDB] = (bf16_t)(p0 >> 16); d[2 * LDB] = (bf16_t)(p1 & 0xffffu); d[3 * LDB] = (bf16_t)(p1 >> 16);
;                     d[4 * LDB] = (bf16_t)(p2 & 0xffffu); d[5 * LDB] = (bf16_t)(p2 >> 16); d[6 * LDB] = (bf16_t)(p3 & 0xffffu); d[7 * LDB] = (bf16_t)(p3 >> 16); }
.LBB0_669:
	v_or_b32_e32 v134, s11, v48
	v_ashrrev_i32_e32 v135, 31, v134
	v_lshlrev_b32_e32 v120, 2, v48
	v_lshlrev_b64 v[48:49], 11, v[134:135]
	v_lshl_add_u64 v[150:151], v[130:131], 0, v[48:49]
	global_load_dword v136, v120, s[20:21]
	global_load_dwordx2 v[140:141], v[150:151], off
	global_load_dwordx2 v[138:139], v[150:151], off offset:32
	s_waitcnt vmcnt(7)
	v_lshlrev_b32_e32 v238, 4, v221
	v_add_u32_e32 v238, 0x11600, v238
	v_and_b32_e32 v239, 0xff, v221
	v_lshlrev_b32_e32 v239, 4, v239
	v_add_u32_e32 v239, 0x13600, v239
	ds_write_b128 v238, v[240:243]
	ds_write_b128 v239, v[244:247]
	s_waitcnt lgkmcnt(0)
	s_barrier
	ds_read_b128 v[16:19], v203 offset:16
	ds_read_b128 v[24:27], v203
	ds_read_b128 v[20:23], v203 offset:4112
	ds_read_b128 v[28:31], v203 offset:4096
	ds_read_b64 v[48:49], v181
	s_waitcnt vmcnt(6)
	v_lshlrev_b32_e32 v50, 16, v44
	v_and_b32_e32 v51, 0xffff0000, v44
	v_lshlrev_b32_e32 v44, 16, v45
	v_and_b32_e32 v45, 0xffff0000, v45
	v_lshlrev_b32_e32 v52, 16, v46
	v_and_b32_e32 v53, 0xffff0000, v46
	v_lshlrev_b32_e32 v54, 16, v47
	v_and_b32_e32 v55, 0xffff0000, v47
	s_waitcnt lgkmcnt(0)
	v_sub_f32_e32 v47, v51, v48
	v_sub_f32_e32 v46, v50, v48
	v_sub_f32_e32 v45, v45, v48
	v_sub_f32_e32 v44, v44, v48
	v_pk_mul_f32 v[46:47], v[48:49], v[46:47] op_sel:[1,0]
	v_pk_mul_f32 v[44:45], v[48:49], v[44:45] op_sel:[1,0]
	s_waitcnt vmcnt(5)
	v_pk_fma_f32 v[46:47], v[24:25], v[46:47], v[28:29]
	v_sub_f32_e32 v51, v55, v48
	v_sub_f32_e32 v50, v54, v48
	v_sub_f32_e32 v53, v53, v48
	v_sub_f32_e32 v52, v52, v48
	v_pk_fma_f32 v[44:45], v[26:27], v[44:45], v[30:31]
	v_pk_mul_f32 v[52:53], v[48:49], v[52:53] op_sel:[1,0]
	v_pk_mul_f32 v[48:49], v[48:49], v[50:51] op_sel:[1,0]
	v_cvt_pk_bf16_f32 v46, v46, v47
	v_pk_fma_f32 v[50:51], v[16:17], v[52:53], v[20:21]
	v_pk_fma_f32 v[48:49], v[18:19], v[48:49], v[22:23]
	v_cvt_pk_bf16_f32 v44, v44, v45
	v_cvt_pk_bf16_f32 v45, v50, v51
	v_lshlrev_b32_e32 v50, 16, v43
	v_cvt_pk_bf16_f32 v47, v48, v49
	ds_write_b16 v186, v46
	ds_write_b16_d16_hi v186, v46 offset:272
	ds_write_b16 v186, v44 offset:544
	ds_write_b16_d16_hi v186, v44 offset:816
	ds_write_b16 v186, v45 offset:1088
	ds_write_b16_d16_hi v186, v45 offset:1360
	ds_write_b16 v186, v47 offset:1632
	ds_write_b16_d16_hi v186, v47 offset:1904
	ds_read_b64 v[44:45], v187
	v_lshlrev_b32_e32 v46, 16, v40
	v_and_b32_e32 v47, 0xffff0000, v40
	v_lshlrev_b32_e32 v40, 16, v41
	v_and_b32_e32 v41, 0xffff0000, v41
	v_lshlrev_b32_e32 v48, 16, v42
	v_and_b32_e32 v49, 0xffff0000, v42
	v_and_b32_e32 v51, 0xffff0000, v43
	s_waitcnt lgkmcnt(0)
	v_sub_f32_e32 v43, v47, v44
	v_sub_f32_e32 v42, v46, v44
	v_sub_f32_e32 v41, v41, v44
	v_sub_f32_e32 v40, v40, v44
	v_pk_mul_f32 v[42:43], v[44:45], v[42:43] op_sel:[1,0]
	v_pk_mul_f32 v[40:41], v[44:45], v[40:41] op_sel:[1,0]
	v_pk_fma_f32 v[42:43], v[24:25], v[42:43], v[28:29]
	v_sub_f32_e32 v47, v51, v44
	v_sub_f32_e32 v46, v50, v44
	v_sub_f32_e32 v49, v49, v44
	v_sub_f32_e32 v48, v48, v44
	v_pk_fma_f32 v[40:41], v[26:27], v[40:41], v[30:31]
	v_pk_mul_f32 v[48:49], v[44:45], v[48:49] op_sel:[1,0]
	v_pk_mul_f32 v[44:45], v[44:45], v[46:47] op_sel:[1,0]
	v_cvt_pk_bf16_f32 v42, v42, v43
	s_and_b64 vcc, exec, s[4:5]
	v_pk_fma_f32 v[44:45], v[18:19], v[44:45], v[22:23]
	v_pk_fma_f32 v[46:47], v[16:17], v[48:49], v[20:21]
	v_cvt_pk_bf16_f32 v40, v40, v41
	s_nop 0
	v_cvt_pk_bf16_f32 v41, v46, v47
	v_cvt_pk_bf16_f32 v43, v44, v45
	ds_write_b16 v188, v42
	ds_write_b16_d16_hi v188, v42 offset:272
	ds_write_b16 v188, v40 offset:544
	ds_write_b16_d16_hi v188, v40 offset:816
	ds_write_b16 v188, v41 offset:1088
	ds_write_b16_d16_hi v188, v41 offset:1360
	ds_write_b16 v188, v43 offset:1632
	ds_write_b16_d16_hi v188, v43 offset:1904
	s_cbranch_vccnz .LBB0_671
	ds_read_b64 v[40:41], v189
	v_lshlrev_b32_e32 v44, 16, v0
	v_and_b32_e32 v45, 0xffff0000, v0
	v_lshlrev_b32_e32 v42, 16, v1
	v_and_b32_e32 v43, 0xffff0000, v1
	v_lshlrev_b32_e32 v48, 16, v2
	v_and_b32_e32 v49, 0xffff0000, v2
	v_lshlrev_b32_e32 v46, 16, v3
	v_and_b32_e32 v47, 0xffff0000, v3
	s_waitcnt lgkmcnt(0)
	v_sub_f32_e32 v45, v45, v40
	v_sub_f32_e32 v44, v44, v40
	v_sub_f32_e32 v43, v43, v40
	v_sub_f32_e32 v42, v42, v40
	v_pk_mul_f32 v[44:45], v[40:41], v[44:45] op_sel:[1,0]
	v_sub_f32_e32 v47, v47, v40
	v_sub_f32_e32 v46, v46, v40
	v_sub_f32_e32 v49, v49, v40
	v_sub_f32_e32 v48, v48, v40
	v_pk_mul_f32 v[42:43], v[40:41], v[42:43] op_sel:[1,0]
	v_pk_fma_f32 v[44:45], v[24:25], v[44:45], v[28:29]
	v_pk_mul_f32 v[48:49], v[40:41], v[48:49] op_sel:[1,0]
	v_pk_mul_f32 v[40:41], v[40:41], v[46:47] op_sel:[1,0]
	v_pk_fma_f32 v[42:43], v[26:27], v[42:43], v[30:31]
	v_pk_fma_f32 v[40:41], v[18:19], v[40:41], v[22:23]
	v_cvt_pk_bf16_f32 v44, v44, v45
	v_pk_fma_f32 v[46:47], v[16:17], v[48:49], v[20:21]
	v_cvt_pk_bf16_f32 v42, v42, v43
	v_and_b32_e32 v45, 0xffff0000, v4
	v_cvt_pk_bf16_f32 v43, v46, v47
	v_cvt_pk_bf16_f32 v40, v40, v41
	ds_write_b16 v190, v44
	ds_write_b16_d16_hi v190, v44 offset:272
	ds_write_b16 v190, v42 offset:544
	ds_write_b16_d16_hi v190, v42 offset:816
	ds_write_b16 v190, v43 offset:1088
	ds_write_b16_d16_hi v190, v43 offset:1360
	ds_write_b16 v190, v40 offset:1632
	ds_write_b16_d16_hi v190, v40 offset:1904
	ds_read_b64 v[40:41], v191
	v_lshlrev_b32_e32 v42, 16, v5
	v_and_b32_e32 v43, 0xffff0000, v5
	v_lshlrev_b32_e32 v44, 16, v4
	v_lshlrev_b32_e32 v46, 16, v6
	s_waitcnt lgkmcnt(0)
	v_sub_f32_e32 v43, v43, v40
	v_sub_f32_e32 v42, v42, v40
	v_and_b32_e32 v47, 0xffff0000, v6
	v_sub_f32_e32 v45, v45, v40
	v_sub_f32_e32 v44, v44, v40
	v_pk_mul_f32 v[42:43], v[40:41], v[42:43] op_sel:[1,0]
	v_lshlrev_b32_e32 v48, 16, v7
	v_and_b32_e32 v49, 0xffff0000, v7
	v_pk_mul_f32 v[44:45], v[40:41], v[44:45] op_sel:[1,0]
	v_pk_fma_f32 v[26:27], v[26:27], v[42:43], v[30:31]
	v_sub_f32_e32 v31, v47, v40
	v_sub_f32_e32 v30, v46, v40
	v_pk_fma_f32 v[24:25], v[24:25], v[44:45], v[28:29]
	v_sub_f32_e32 v29, v49, v40
	v_sub_f32_e32 v28, v48, v40
	v_pk_mul_f32 v[30:31], v[40:41], v[30:31] op_sel:[1,0]
	v_pk_mul_f32 v[28:29], v[40:41], v[28:29] op_sel:[1,0]
	v_pk_fma_f32 v[16:17], v[16:17], v[30:31], v[20:21]
	v_cvt_pk_bf16_f32 v20, v24, v25
	v_pk_fma_f32 v[18:19], v[18:19], v[28:29], v[22:23]
	v_cvt_pk_bf16_f32 v21, v26, v27
	v_cvt_pk_bf16_f32 v16, v16, v17
	s_nop 0
	v_cvt_pk_bf16_f32 v17, v18, v19
	ds_write_b16 v192, v20
	ds_write_b16_d16_hi v192, v20 offset:272
	ds_write_b16 v192, v21 offset:544
	ds_write_b16_d16_hi v192, v21 offset:816
	ds_write_b16 v192, v16 offset:1088
	ds_write_b16_d16_hi v192, v16 offset:1360
	ds_write_b16 v192, v17 offset:1632
	ds_write_b16_d16_hi v192, v17 offset:1904

.LBB0_675:
	s_nop 0
	ds_read_b128 v[40:43], v203 offset:528
	ds_read_b128 v[48:51], v203 offset:512
	ds_read_b128 v[44:47], v203 offset:4624
	ds_read_b128 v[52:55], v203 offset:4608
	v_add_co_u32_e32 v16, vcc, 0x8000, v148
	s_waitcnt vmcnt(5)
	v_mov_b64_e32 v[28:29], v[36:37]
	v_addc_co_u32_e32 v17, vcc, 0, v149, vcc
	global_load_dwordx4 v[20:23], v[16:17], off
	s_nop 0
	global_load_dwordx4 v[16:19], v[16:17], off offset:64
	s_and_b64 vcc, exec, s[4:5]
	v_mov_b64_e32 v[30:31], v[38:39]
	s_cbranch_vccnz .LBB0_677
	v_add_co_u32_e32 v24, vcc, 0x8000, v148
	s_nop 1
	v_addc_co_u32_e32 v25, vcc, 0, v149, vcc
	global_load_dwordx4 v[28:31], v[24:25], off offset:128

.LBB0_689:
	s_nop 0
	ds_read_b128 v[36:39], v203 offset:1040
	ds_read_b128 v[52:55], v203 offset:1024
	ds_read_b128 v[48:51], v203 offset:5136
	ds_read_b128 v[60:63], v203 offset:5120
	v_add_co_u32_e32 v32, vcc, 0x10000, v148
	s_waitcnt vmcnt(5)
	v_mov_b64_e32 v[46:47], v[30:31]
	v_addc_co_u32_e32 v33, vcc, 0, v149, vcc
	global_load_dwordx4 v[56:59], v[32:33], off
	global_load_dwordx4 v[40:43], v[32:33], off offset:64
	s_and_b64 vcc, exec, s[4:5]
	v_mov_b64_e32 v[44:45], v[28:29]
	s_cbranch_vccnz .LBB0_691
	v_add_co_u32_e32 v32, vcc, 0x10000, v148
	s_nop 1
	v_addc_co_u32_e32 v33, vcc, 0, v149, vcc
	global_load_dwordx4 v[44:47], v[32:33], off offset:128

.LBB0_703:
	s_nop 0
	ds_read_b128 v[60:63], v203 offset:1552
	ds_read_b128 v[72:75], v203 offset:1536
	ds_read_b128 v[68:71], v203 offset:5648
	ds_read_b128 v[76:79], v203 offset:5632
	v_add_co_u32_e32 v24, vcc, 0x18000, v148
	s_waitcnt vmcnt(5)
	v_mov_b64_e32 v[54:55], v[46:47]
	v_addc_co_u32_e32 v25, vcc, 0, v149, vcc
	global_load_dwordx4 v[64:67], v[24:25], off
	global_load_dwordx4 v[48:51], v[24:25], off offset:64
	s_and_b64 vcc, exec, s[4:5]
	v_mov_b64_e32 v[52:53], v[44:45]
	s_cbranch_vccnz .LBB0_705
	v_add_co_u32_e32 v24, vcc, 0x18000, v148
	s_nop 1
	v_addc_co_u32_e32 v25, vcc, 0, v149, vcc
	global_load_dwordx4 v[52:55], v[24:25], off offset:128

.LBB0_717:
	s_nop 0
	ds_read_b128 v[68:71], v203 offset:2064
	ds_read_b128 v[80:83], v203 offset:2048
	ds_read_b128 v[76:79], v203 offset:6160
	ds_read_b128 v[84:87], v203 offset:6144
	v_add_co_u32_e32 v32, vcc, 0x20000, v148
	s_waitcnt vmcnt(5)
	v_mov_b64_e32 v[62:63], v[54:55]
	v_addc_co_u32_e32 v33, vcc, 0, v149, vcc
	global_load_dwordx4 v[72:75], v[32:33], off
	global_load_dwordx4 v[56:59], v[32:33], off offset:64
	s_and_b64 vcc, exec, s[4:5]
	v_mov_b64_e32 v[60:61], v[52:53]
	s_cbranch_vccnz .LBB0_719
	v_add_co_u32_e32 v32, vcc, 0x20000, v148
	s_nop 1
	v_addc_co_u32_e32 v33, vcc, 0, v149, vcc
	global_load_dwordx4 v[60:63], v[32:33], off offset:128

.LBB0_731:
	s_nop 0
	ds_read_b128 v[76:79], v203 offset:2576
	ds_read_b128 v[88:91], v203 offset:2560
	ds_read_b128 v[80:83], v203 offset:6672
	ds_read_b128 v[92:95], v203 offset:6656
	v_add_co_u32_e32 v36, vcc, 0x28000, v148
	s_waitcnt vmcnt(5)
	v_mov_b64_e32 v[70:71], v[62:63]
	v_addc_co_u32_e32 v37, vcc, 0, v149, vcc
	global_load_dwordx4 v[84:87], v[36:37], off
	global_load_dwordx4 v[64:67], v[36:37], off offset:64
	s_and_b64 vcc, exec, s[4:5]
	v_mov_b64_e32 v[68:69], v[60:61]
	s_cbranch_vccnz .LBB0_733
	v_add_co_u32_e32 v36, vcc, 0x28000, v148
	s_nop 1
	v_addc_co_u32_e32 v37, vcc, 0, v149, vcc
	global_load_dwordx4 v[68:71], v[36:37], off offset:128

.LBB0_745:
	s_nop 0
	ds_read_b128 v[32:35], v203 offset:3088
	ds_read_b128 v[96:99], v203 offset:3072
	ds_read_b128 v[92:95], v203 offset:7184
	ds_read_b128 v[100:103], v203 offset:7168
	v_add_co_u32_e32 v56, vcc, 0x30000, v148
	s_waitcnt vmcnt(5)
	v_mov_b64_e32 v[82:83], v[70:71]
	v_addc_co_u32_e32 v57, vcc, 0, v149, vcc
	global_load_dwordx4 v[88:91], v[56:57], off
	global_load_dwordx4 v[76:79], v[56:57], off offset:64
	s_and_b64 vcc, exec, s[4:5]
	v_mov_b64_e32 v[80:81], v[68:69]
	s_cbranch_vccnz .LBB0_747
	v_add_co_u32_e32 v56, vcc, 0x30000, v148
	s_nop 1
	v_addc_co_u32_e32 v57, vcc, 0, v149, vcc
	global_load_dwordx4 v[80:83], v[56:57], off offset:128

.LBB0_759:
	s_nop 0
	ds_read_b128 v[96:99], v203 offset:3600
	ds_read_b128 v[104:107], v203 offset:3584
	ds_read_b128 v[100:103], v203 offset:7696
	ds_read_b128 v[108:111], v203 offset:7680
	v_add_co_u32_e32 v32, vcc, 0x38000, v148
	s_waitcnt vmcnt(5)
	v_mov_b64_e32 v[36:37], v[80:81]
	v_addc_co_u32_e32 v33, vcc, 0, v149, vcc
	global_load_dwordx4 v[92:95], v[32:33], off
	global_load_dwordx4 v[84:87], v[32:33], off offset:64
	s_and_b64 vcc, exec, s[4:5]
	v_mov_b64_e32 v[38:39], v[82:83]
	s_cbranch_vccnz .LBB0_761
	v_add_co_u32_e32 v32, vcc, 0x38000, v148
	s_nop 1
	v_addc_co_u32_e32 v33, vcc, 0, v149, vcc
	global_load_dwordx4 v[36:39], v[32:33], off offset:128
